# cand33 + attention out-projection GEMM epilogue: bias quads requested at the unit-loop head
# baseline (speedup 1.0000x reference)
.LBB0_1514:
	v_lshl_or_b32 v235, s63, 8, v168
	v_lshlrev_b32_e32 v235, 2, v235
	s_and_b64 vcc, exec, s[6:7]
	s_cbranch_vccz .Lp11b_skip
	global_load_dwordx4 v[236:239], v235, s[4:5]
	global_load_dwordx4 v[240:243], v235, s[4:5] offset:16
	global_load_dwordx4 v[244:247], v235, s[4:5] offset:512
	global_load_dwordx4 v[248:251], v235, s[4:5] offset:528

.LBB0_1524:
	v_lshl_or_b32 v162, s63, 8, v168
	v_ashrrev_i32_e32 v163, 31, v162
	v_cndmask_b32_e64 v131, 0, 1, s[6:7]
	v_lshl_add_u64 v[164:165], v[162:163], 2, s[4:5]
	v_mov_b32_e32 v130, 0
	v_cmp_ne_u32_e64 s[2:3], 1, v131
	s_andn2_b64 vcc, exec, s[6:7]
	v_mov_b32_e32 v134, 0
	v_mov_b32_e32 v135, 0
	v_mov_b32_e32 v136, 0
	v_mov_b32_e32 v137, 0
	s_cbranch_vccnz .LBB0_1526
	v_mov_b64_e32 v[134:135], v[236:237]
	v_mov_b64_e32 v[136:137], v[238:239]
.LBB0_1526:
	s_and_b64 vcc, exec, s[2:3]
	v_mov_b32_e32 v131, 0
	v_mov_b32_e32 v132, 0
	v_mov_b32_e32 v133, 0
	s_cbranch_vccnz .LBB0_1528
	v_mov_b64_e32 v[130:131], v[240:241]
	v_mov_b64_e32 v[132:133], v[242:243]
.LBB0_1528:
	v_mov_b32_e32 v138, 0
	s_and_b64 vcc, exec, s[2:3]
	v_mov_b32_e32 v142, 0
	v_mov_b32_e32 v143, 0
	v_mov_b32_e32 v144, 0
	v_mov_b32_e32 v145, 0
	s_cbranch_vccnz .LBB0_1530
	v_mov_b64_e32 v[142:143], v[244:245]
	v_mov_b64_e32 v[144:145], v[246:247]
.LBB0_1530:
	s_and_b64 vcc, exec, s[2:3]
	v_mov_b32_e32 v139, 0
	v_mov_b32_e32 v140, 0
	v_mov_b32_e32 v141, 0
	s_cbranch_vccnz .LBB0_1532
	v_mov_b64_e32 v[138:139], v[248:249]
	v_mov_b64_e32 v[140:141], v[250:251]
.LBB0_1532:
	v_lshl_add_u32 v164, s36, 8, v166
	v_ashrrev_i32_e32 v165, 31, v164
	v_lshlrev_b64 v[172:173], 13, v[164:165]
	v_lshl_add_u64 v[172:173], s[14:15], 0, v[172:173]
	v_lshlrev_b64 v[174:175], 1, v[162:163]
	v_lshl_add_u64 v[162:163], v[172:173], 0, v[174:175]
	v_pk_add_f32 v[128:129], v[128:129], v[136:137]
	v_pk_add_f32 v[126:127], v[126:127], v[134:135]
	v_pk_add_f32 v[172:173], v[124:125], v[132:133]
	v_pk_add_f32 v[124:125], v[122:123], v[130:131]
	v_cvt_pk_bf16_f32 v122, v126, v127
	v_cvt_pk_bf16_f32 v123, v128, v129
	v_pk_add_f32 v[118:119], v[118:119], v[142:143]
	v_cvt_pk_bf16_f32 v124, v124, v125
	v_cvt_pk_bf16_f32 v125, v172, v173
	global_store_dwordx4 v[162:163], v[122:125], off
	v_pk_add_f32 v[120:121], v[120:121], v[144:145]
	v_pk_add_f32 v[114:115], v[114:115], v[134:135]
	v_pk_add_f32 v[122:123], v[112:113], v[140:141]
	v_pk_add_f32 v[112:113], v[110:111], v[138:139]
	v_cvt_pk_bf16_f32 v110, v118, v119
	v_cvt_pk_bf16_f32 v111, v120, v121
	v_pk_add_f32 v[102:103], v[102:103], v[142:143]
	v_cvt_pk_bf16_f32 v112, v112, v113
	v_cvt_pk_bf16_f32 v113, v122, v123
	global_store_dwordx4 v[162:163], v[110:113], off offset:256
	v_pk_add_f32 v[104:105], v[104:105], v[144:145]
	v_pk_add_f32 v[98:99], v[98:99], v[134:135]
	v_or_b32_e32 v110, 16, v164
	v_ashrrev_i32_e32 v111, 31, v110
	v_lshlrev_b64 v[110:111], 13, v[110:111]
	v_lshl_add_u64 v[110:111], s[14:15], 0, v[110:111]
	v_lshl_add_u64 v[110:111], v[110:111], 0, v[174:175]
	v_pk_add_f32 v[112:113], v[116:117], v[136:137]
	v_pk_add_f32 v[116:117], v[108:109], v[132:133]
	v_pk_add_f32 v[108:109], v[106:107], v[130:131]
	v_cvt_pk_bf16_f32 v106, v114, v115
	v_cvt_pk_bf16_f32 v107, v112, v113
	v_pk_add_f32 v[86:87], v[86:87], v[142:143]
	v_cvt_pk_bf16_f32 v108, v108, v109
	v_cvt_pk_bf16_f32 v109, v116, v117
	global_store_dwordx4 v[110:111], v[106:109], off
	v_pk_add_f32 v[88:89], v[88:89], v[144:145]
	v_pk_add_f32 v[82:83], v[82:83], v[134:135]
	v_pk_add_f32 v[106:107], v[96:97], v[140:141]
	v_pk_add_f32 v[96:97], v[94:95], v[138:139]
	v_cvt_pk_bf16_f32 v94, v102, v103
	v_cvt_pk_bf16_f32 v95, v104, v105
	v_pk_add_f32 v[72:73], v[72:73], v[144:145]
	v_cvt_pk_bf16_f32 v96, v96, v97
	v_cvt_pk_bf16_f32 v97, v106, v107
	global_store_dwordx4 v[110:111], v[94:97], off offset:256
	v_pk_add_f32 v[70:71], v[70:71], v[142:143]
	v_pk_add_f32 v[62:63], v[62:63], v[134:135]
	v_or_b32_e32 v94, 32, v164
	v_ashrrev_i32_e32 v95, 31, v94
	v_lshlrev_b64 v[94:95], 13, v[94:95]
	v_lshl_add_u64 v[94:95], s[14:15], 0, v[94:95]
	v_lshl_add_u64 v[94:95], v[94:95], 0, v[174:175]
	v_pk_add_f32 v[96:97], v[100:101], v[136:137]
	v_pk_add_f32 v[100:101], v[92:93], v[132:133]
	v_pk_add_f32 v[92:93], v[90:91], v[130:131]
	v_cvt_pk_bf16_f32 v90, v98, v99
	v_cvt_pk_bf16_f32 v91, v96, v97
	v_pk_add_f32 v[64:65], v[64:65], v[136:137]
	v_cvt_pk_bf16_f32 v92, v92, v93
	v_cvt_pk_bf16_f32 v93, v100, v101
	global_store_dwordx4 v[94:95], v[90:93], off
	v_pk_add_f32 v[56:57], v[56:57], v[144:145]
	v_pk_add_f32 v[54:55], v[54:55], v[142:143]
	v_pk_add_f32 v[90:91], v[80:81], v[140:141]
	v_pk_add_f32 v[80:81], v[78:79], v[138:139]
	v_cvt_pk_bf16_f32 v78, v86, v87
	v_cvt_pk_bf16_f32 v79, v88, v89
	v_pk_add_f32 v[50:51], v[50:51], v[134:135]
	v_cvt_pk_bf16_f32 v80, v80, v81
	v_cvt_pk_bf16_f32 v81, v90, v91
	global_store_dwordx4 v[94:95], v[78:81], off offset:256
	v_pk_add_f32 v[40:41], v[40:41], v[144:145]
	v_pk_add_f32 v[38:39], v[38:39], v[142:143]
	v_or_b32_e32 v78, 48, v164
	v_ashrrev_i32_e32 v79, 31, v78
	v_lshlrev_b64 v[78:79], 13, v[78:79]
	v_lshl_add_u64 v[78:79], s[14:15], 0, v[78:79]
	v_lshl_add_u64 v[78:79], v[78:79], 0, v[174:175]
	v_pk_add_f32 v[80:81], v[84:85], v[136:137]
	v_pk_add_f32 v[84:85], v[76:77], v[132:133]
	v_pk_add_f32 v[76:77], v[74:75], v[130:131]
	v_cvt_pk_bf16_f32 v74, v82, v83
	v_cvt_pk_bf16_f32 v75, v80, v81
	v_pk_add_f32 v[34:35], v[34:35], v[134:135]
	v_cvt_pk_bf16_f32 v76, v76, v77
	v_cvt_pk_bf16_f32 v77, v84, v85
	global_store_dwordx4 v[78:79], v[74:77], off
	v_pk_add_f32 v[24:25], v[24:25], v[144:145]
	v_pk_add_f32 v[22:23], v[22:23], v[142:143]
	v_pk_add_f32 v[74:75], v[68:69], v[140:141]
	v_pk_add_f32 v[68:69], v[66:67], v[138:139]
	v_cvt_pk_bf16_f32 v66, v70, v71
	v_cvt_pk_bf16_f32 v67, v72, v73
	v_pk_add_f32 v[18:19], v[18:19], v[134:135]
	v_cvt_pk_bf16_f32 v68, v68, v69
	v_cvt_pk_bf16_f32 v69, v74, v75
	global_store_dwordx4 v[78:79], v[66:69], off offset:256
	v_pk_add_f32 v[8:9], v[8:9], v[144:145]
	v_pk_add_f32 v[6:7], v[6:7], v[142:143]
	v_pk_add_f32 v[68:69], v[60:61], v[132:133]
	v_pk_add_f32 v[60:61], v[58:59], v[130:131]
	v_cvt_pk_bf16_f32 v58, v62, v63
	v_add_co_u32_e32 v62, vcc, s59, v162
	v_cvt_pk_bf16_f32 v59, v64, v65
	v_cvt_pk_bf16_f32 v60, v60, v61
	v_cvt_pk_bf16_f32 v61, v68, v69
	v_lshl_add_u64 v[66:67], v[162:163], 0, s[10:11]
	s_nop 0
	v_addc_co_u32_e32 v63, vcc, 0, v163, vcc
	global_store_dwordx4 v[62:63], v[58:61], off
	s_nop 1
	v_pk_add_f32 v[58:59], v[48:49], v[140:141]
	v_pk_add_f32 v[48:49], v[46:47], v[138:139]
	v_cvt_pk_bf16_f32 v46, v54, v55
	v_cvt_pk_bf16_f32 v47, v56, v57
	s_nop 0
	v_cvt_pk_bf16_f32 v48, v48, v49
	v_cvt_pk_bf16_f32 v49, v58, v59
	global_store_dwordx4 v[66:67], v[46:49], off offset:256
	s_nop 1
	v_pk_add_f32 v[48:49], v[52:53], v[136:137]
	v_pk_add_f32 v[52:53], v[44:45], v[132:133]
	v_pk_add_f32 v[44:45], v[42:43], v[130:131]
	v_cvt_pk_bf16_f32 v42, v50, v51
	v_cvt_pk_bf16_f32 v43, v48, v49
	v_add_co_u32_e32 v48, vcc, s60, v162
	v_cvt_pk_bf16_f32 v44, v44, v45
	v_cvt_pk_bf16_f32 v45, v52, v53
	v_lshl_add_u64 v[46:47], v[162:163], 0, s[20:21]
	s_nop 0
	v_addc_co_u32_e32 v49, vcc, 0, v163, vcc
	global_store_dwordx4 v[48:49], v[42:45], off
	s_nop 1
	v_pk_add_f32 v[42:43], v[32:33], v[140:141]
	v_pk_add_f32 v[32:33], v[30:31], v[138:139]
	v_cvt_pk_bf16_f32 v30, v38, v39
	v_cvt_pk_bf16_f32 v31, v40, v41
	s_nop 0
	v_cvt_pk_bf16_f32 v32, v32, v33
	v_cvt_pk_bf16_f32 v33, v42, v43
	global_store_dwordx4 v[46:47], v[30:33], off offset:256
	s_nop 1
	v_pk_add_f32 v[32:33], v[36:37], v[136:137]
	v_pk_add_f32 v[36:37], v[28:29], v[132:133]
	v_pk_add_f32 v[28:29], v[26:27], v[130:131]
	v_cvt_pk_bf16_f32 v26, v34, v35
	v_cvt_pk_bf16_f32 v27, v32, v33
	v_add_co_u32_e32 v32, vcc, s61, v162
	v_cvt_pk_bf16_f32 v28, v28, v29
	v_cvt_pk_bf16_f32 v29, v36, v37
	v_lshl_add_u64 v[30:31], v[162:163], 0, s[22:23]
	s_nop 0
	v_addc_co_u32_e32 v33, vcc, 0, v163, vcc
	global_store_dwordx4 v[32:33], v[26:29], off
	s_nop 1
	v_pk_add_f32 v[26:27], v[16:17], v[140:141]
	v_pk_add_f32 v[16:17], v[14:15], v[138:139]
	v_cvt_pk_bf16_f32 v14, v22, v23
	v_cvt_pk_bf16_f32 v15, v24, v25
	s_nop 0
	v_cvt_pk_bf16_f32 v16, v16, v17
	v_cvt_pk_bf16_f32 v17, v26, v27
	global_store_dwordx4 v[30:31], v[14:17], off offset:256
	s_nop 1
	v_pk_add_f32 v[16:17], v[20:21], v[136:137]
	v_pk_add_f32 v[20:21], v[12:13], v[132:133]
	v_pk_add_f32 v[12:13], v[10:11], v[130:131]
	v_cvt_pk_bf16_f32 v10, v18, v19
	v_cvt_pk_bf16_f32 v11, v16, v17
	v_add_co_u32_e32 v16, vcc, s62, v162
	v_lshl_add_u64 v[14:15], v[162:163], 0, s[24:25]
	s_nop 0
	v_addc_co_u32_e32 v17, vcc, 0, v163, vcc
	v_cvt_pk_bf16_f32 v12, v12, v13
	v_cvt_pk_bf16_f32 v13, v20, v21
	global_store_dwordx4 v[16:17], v[10:13], off
	s_andn2_b64 vcc, exec, s[0:1]
	s_mov_b64 s[0:1], -1
	v_pk_add_f32 v[10:11], v[4:5], v[140:141]
	v_pk_add_f32 v[4:5], v[2:3], v[138:139]
	v_cvt_pk_bf16_f32 v2, v6, v7
	v_cvt_pk_bf16_f32 v3, v8, v9
	s_nop 0
	v_cvt_pk_bf16_f32 v4, v4, v5
	v_cvt_pk_bf16_f32 v5, v10, v11
	global_store_dwordx4 v[14:15], v[2:5], off offset:256
	s_cbranch_vccnz .LBB0_1513
	s_andn2_b64 vcc, exec, s[12:13]
	s_cbranch_vccnz .LBB0_1512
	s_barrier
	s_branch .LBB0_1512
